# V45 + GDN scan steady-state loop body copy with exact vmcnt(56) (10-deep prefetch ring no longer throttled)
# baseline (speedup 1.0000x reference)
.LBB0_907:
	s_add_i32 s34, s34, 10
	s_add_i32 s4, s4, 0xa000
	s_add_u32 s6, s6, 0x14000
	s_addc_u32 s7, s7, 0
	s_and_b64 vcc, exec, s[8:9]
	s_cbranch_vccnz .LBB0_930
	s_cmpk_lt_u32 s34, 0x65
	s_cbranch_scc1 .Lgs_fast

.Lgs_fast:
	v_lshl_add_u64 v[190:191], v[188:189], 0, s[6:7]
	v_cvt_pk_bf16_f32 v164, v164, v165
	v_cvt_pk_bf16_f32 v165, v166, v167
	v_cvt_pk_bf16_f32 v167, v170, v171
	v_cvt_pk_bf16_f32 v170, v160, v161
	v_add_co_u32_e32 v160, vcc, s11, v190
	v_cvt_pk_bf16_f32 v166, v168, v169
	v_cvt_pk_bf16_f32 v168, v172, v173
	v_cvt_pk_bf16_f32 v169, v174, v175
	v_cvt_pk_bf16_f32 v171, v162, v163
	v_addc_co_u32_e32 v161, vcc, 0, v191, vcc
	ds_write_b64 v193, v[164:165]
	ds_write_b64 v193, v[166:167] offset:2304
	ds_write_b64 v193, v[168:169] offset:4608
	ds_write_b64 v194, v[170:171]
	global_store_dwordx4 v[160:161], v[164:167], off
	global_store_dwordx4 v[160:161], v[168:171], off offset:16
	s_waitcnt lgkmcnt(0)
	s_barrier
	ds_read_b128 v[164:167], v195
	ds_read_b128 v[168:171], v195 offset:64
	s_waitcnt vmcnt(56)
	v_lshlrev_b32_e32 v160, 16, v12
	v_and_b32_e32 v161, 0xffff0000, v12
	v_lshlrev_b32_e32 v162, 16, v13
	v_and_b32_e32 v163, 0xffff0000, v13
	ds_read_b128 v[172:175], v195 offset:2368
	ds_read_b128 v[198:201], v195 offset:4672
	s_waitcnt lgkmcnt(3)
	v_mfma_f32_16x16x32_bf16 v[160:163], v[0:3], v[164:167], v[160:163]
	v_lshlrev_b32_e32 v164, 16, v14
	v_and_b32_e32 v165, 0xffff0000, v14
	v_lshlrev_b32_e32 v166, 16, v15
	s_waitcnt lgkmcnt(2)
	v_mfma_f32_16x16x32_bf16 v[160:163], v[4:7], v[168:171], v[160:163]
	ds_read_b128 v[168:171], v195 offset:2304
	v_and_b32_e32 v167, 0xffff0000, v15
	ds_read_b128 v[202:205], v196 offset:64
	s_cmpk_lt_u32 s34, 0x76
	s_waitcnt lgkmcnt(1)
	v_mfma_f32_16x16x32_bf16 v[164:167], v[0:3], v[168:171], v[164:167]
	v_lshlrev_b32_e32 v168, 16, v8
	v_and_b32_e32 v169, 0xffff0000, v8
	v_lshlrev_b32_e32 v170, 16, v9
	v_mfma_f32_16x16x32_bf16 v[164:167], v[4:7], v[172:175], v[164:167]
	ds_read_b128 v[172:175], v195 offset:4608
	v_and_b32_e32 v171, 0xffff0000, v9
	s_cselect_b64 s[8:9], -1, 0
	s_and_b64 vcc, exec, s[8:9]
	s_waitcnt lgkmcnt(0)
	v_mfma_f32_16x16x32_bf16 v[168:171], v[0:3], v[172:175], v[168:171]
	v_lshlrev_b32_e32 v172, 16, v10
	v_and_b32_e32 v173, 0xffff0000, v10
	v_lshlrev_b32_e32 v174, 16, v11
	v_mfma_f32_16x16x32_bf16 v[168:171], v[4:7], v[198:201], v[168:171]
	ds_read_b128 v[198:201], v196
	v_and_b32_e32 v175, 0xffff0000, v11
	s_waitcnt lgkmcnt(0)
	s_nop 0
	v_mfma_f32_16x16x32_bf16 v[172:175], v[0:3], v[198:201], v[172:175]
	v_mfma_f32_16x16x32_bf16 v[172:175], v[4:7], v[202:205], v[172:175]
	s_cbranch_vccz .Lgs_910
	s_add_i32 s0, s4, 0xffff7000
	s_lshl_b64 s[24:25], s[0:1], 1
	v_lshl_add_u64 v[4:5], v[176:177], 0, s[24:25]
	v_lshl_add_u64 v[12:13], v[178:179], 0, s[24:25]
	global_load_dwordx4 v[0:3], v[4:5], off
	s_nop 0
	global_load_dwordx4 v[4:7], v[4:5], off offset:64
	s_nop 0
	global_load_dwordx4 v[8:11], v[12:13], off offset:16
	s_nop 0
	global_load_dwordx4 v[12:15], v[12:13], off
.Lgs_910:
	v_cvt_pk_bf16_f32 v160, v160, v161
	v_cvt_pk_bf16_f32 v161, v162, v163
	v_cvt_pk_bf16_f32 v162, v164, v165
	v_cvt_pk_bf16_f32 v164, v168, v169
	v_add_co_u32_e32 v168, vcc, s12, v190
	v_cvt_pk_bf16_f32 v163, v166, v167
	v_cvt_pk_bf16_f32 v165, v170, v171
	v_cvt_pk_bf16_f32 v166, v172, v173
	v_cvt_pk_bf16_f32 v167, v174, v175
	v_addc_co_u32_e32 v169, vcc, 0, v191, vcc
	ds_write_b64 v193, v[160:161] offset:9216
	ds_write_b64 v193, v[162:163] offset:11520
	ds_write_b64 v193, v[164:165] offset:13824
	ds_write_b64 v194, v[166:167] offset:9216
	global_store_dwordx4 v[168:169], v[160:163], off
	global_store_dwordx4 v[168:169], v[164:167], off offset:16
	s_waitcnt lgkmcnt(0)
	s_barrier
	ds_read_b128 v[164:167], v195 offset:9216
	ds_read_b128 v[168:171], v195 offset:9280
	s_waitcnt vmcnt(56)
	v_lshlrev_b32_e32 v160, 16, v28
	v_and_b32_e32 v161, 0xffff0000, v28
	v_lshlrev_b32_e32 v162, 16, v29
	v_and_b32_e32 v163, 0xffff0000, v29
	ds_read_b128 v[172:175], v195 offset:11584
	ds_read_b128 v[198:201], v195 offset:13888
	s_waitcnt lgkmcnt(3)
	v_mfma_f32_16x16x32_bf16 v[160:163], v[16:19], v[164:167], v[160:163]
	v_lshlrev_b32_e32 v164, 16, v30
	v_and_b32_e32 v165, 0xffff0000, v30
	v_lshlrev_b32_e32 v166, 16, v31
	s_waitcnt lgkmcnt(2)
	v_mfma_f32_16x16x32_bf16 v[160:163], v[20:23], v[168:171], v[160:163]
	ds_read_b128 v[168:171], v195 offset:11520
	v_and_b32_e32 v167, 0xffff0000, v31
	ds_read_b128 v[202:205], v196 offset:9280
	s_andn2_b64 vcc, exec, s[8:9]
	s_waitcnt lgkmcnt(1)
	v_mfma_f32_16x16x32_bf16 v[164:167], v[16:19], v[168:171], v[164:167]
	v_lshlrev_b32_e32 v168, 16, v24
	v_and_b32_e32 v169, 0xffff0000, v24
	v_lshlrev_b32_e32 v170, 16, v25
	v_mfma_f32_16x16x32_bf16 v[164:167], v[20:23], v[172:175], v[164:167]
	ds_read_b128 v[172:175], v195 offset:13824
	v_and_b32_e32 v171, 0xffff0000, v25
	s_waitcnt lgkmcnt(0)
	s_nop 0
	v_mfma_f32_16x16x32_bf16 v[168:171], v[16:19], v[172:175], v[168:171]
	v_lshlrev_b32_e32 v172, 16, v26
	v_and_b32_e32 v173, 0xffff0000, v26
	v_lshlrev_b32_e32 v174, 16, v27
	v_mfma_f32_16x16x32_bf16 v[168:171], v[20:23], v[198:201], v[168:171]
	ds_read_b128 v[198:201], v196 offset:9216
	v_and_b32_e32 v175, 0xffff0000, v27
	s_waitcnt lgkmcnt(0)
	s_nop 0
	v_mfma_f32_16x16x32_bf16 v[172:175], v[16:19], v[198:201], v[172:175]
	v_mfma_f32_16x16x32_bf16 v[172:175], v[20:23], v[202:205], v[172:175]
	s_cbranch_vccnz .Lgs_912
	s_add_i32 s0, s4, 0xffff8000
	s_lshl_b64 s[8:9], s[0:1], 1
	v_lshl_add_u64 v[20:21], v[176:177], 0, s[8:9]
	v_lshl_add_u64 v[28:29], v[178:179], 0, s[8:9]
	global_load_dwordx4 v[16:19], v[20:21], off
	s_nop 0
	global_load_dwordx4 v[20:23], v[20:21], off offset:64
	s_nop 0
	global_load_dwordx4 v[24:27], v[28:29], off offset:16
	s_nop 0
	global_load_dwordx4 v[28:31], v[28:29], off
.Lgs_912:
	v_cvt_pk_bf16_f32 v160, v160, v161
	v_cvt_pk_bf16_f32 v161, v162, v163
	v_cvt_pk_bf16_f32 v162, v164, v165
	v_cvt_pk_bf16_f32 v164, v168, v169
	v_add_co_u32_e32 v168, vcc, s13, v190
	v_cvt_pk_bf16_f32 v163, v166, v167
	v_cvt_pk_bf16_f32 v165, v170, v171
	v_cvt_pk_bf16_f32 v166, v172, v173
	v_cvt_pk_bf16_f32 v167, v174, v175
	v_addc_co_u32_e32 v169, vcc, 0, v191, vcc
	ds_write_b64 v193, v[160:161]
	ds_write_b64 v193, v[162:163] offset:2304
	ds_write_b64 v193, v[164:165] offset:4608
	ds_write_b64 v194, v[166:167]
	global_store_dwordx4 v[168:169], v[160:163], off
	global_store_dwordx4 v[168:169], v[164:167], off offset:16
	s_waitcnt lgkmcnt(0)
	s_barrier
	ds_read_b128 v[164:167], v195
	ds_read_b128 v[168:171], v195 offset:64
	s_waitcnt vmcnt(56)
	v_lshlrev_b32_e32 v160, 16, v44
	v_and_b32_e32 v161, 0xffff0000, v44
	v_lshlrev_b32_e32 v162, 16, v45
	v_and_b32_e32 v163, 0xffff0000, v45
	ds_read_b128 v[172:175], v195 offset:2368
	ds_read_b128 v[198:201], v195 offset:4672
	s_waitcnt lgkmcnt(3)
	v_mfma_f32_16x16x32_bf16 v[160:163], v[32:35], v[164:167], v[160:163]
	v_lshlrev_b32_e32 v164, 16, v46
	v_and_b32_e32 v165, 0xffff0000, v46
	v_lshlrev_b32_e32 v166, 16, v47
	s_waitcnt lgkmcnt(2)
	v_mfma_f32_16x16x32_bf16 v[160:163], v[36:39], v[168:171], v[160:163]
	ds_read_b128 v[168:171], v195 offset:2304
	v_and_b32_e32 v167, 0xffff0000, v47
	ds_read_b128 v[202:205], v196 offset:64
	s_cmpk_gt_u32 s34, 0x73
	s_waitcnt lgkmcnt(1)
	v_mfma_f32_16x16x32_bf16 v[164:167], v[32:35], v[168:171], v[164:167]
	v_lshlrev_b32_e32 v168, 16, v40
	v_and_b32_e32 v169, 0xffff0000, v40
	v_lshlrev_b32_e32 v170, 16, v41
	v_mfma_f32_16x16x32_bf16 v[164:167], v[36:39], v[172:175], v[164:167]
	ds_read_b128 v[172:175], v195 offset:4608
	v_and_b32_e32 v171, 0xffff0000, v41
	s_waitcnt lgkmcnt(0)
	s_nop 0
	v_mfma_f32_16x16x32_bf16 v[168:171], v[32:35], v[172:175], v[168:171]
	v_lshlrev_b32_e32 v172, 16, v42
	v_and_b32_e32 v173, 0xffff0000, v42
	v_lshlrev_b32_e32 v174, 16, v43
	v_mfma_f32_16x16x32_bf16 v[168:171], v[36:39], v[198:201], v[168:171]
	ds_read_b128 v[198:201], v196
	v_and_b32_e32 v175, 0xffff0000, v43
	s_waitcnt lgkmcnt(0)
	s_nop 0
	v_mfma_f32_16x16x32_bf16 v[172:175], v[32:35], v[198:201], v[172:175]
	v_mfma_f32_16x16x32_bf16 v[172:175], v[36:39], v[202:205], v[172:175]
	s_cbranch_scc1 .Lgs_914
	s_add_i32 s0, s4, 0xffff9000
	s_lshl_b64 s[8:9], s[0:1], 1
	v_lshl_add_u64 v[36:37], v[176:177], 0, s[8:9]
	v_lshl_add_u64 v[44:45], v[178:179], 0, s[8:9]
	global_load_dwordx4 v[32:35], v[36:37], off
	s_nop 0
	global_load_dwordx4 v[36:39], v[36:37], off offset:64
	s_nop 0
	global_load_dwordx4 v[40:43], v[44:45], off offset:16
	s_nop 0
	global_load_dwordx4 v[44:47], v[44:45], off
.Lgs_914:
	v_cvt_pk_bf16_f32 v160, v160, v161
	v_cvt_pk_bf16_f32 v161, v162, v163
	v_cvt_pk_bf16_f32 v162, v164, v165
	v_cvt_pk_bf16_f32 v164, v168, v169
	v_add_co_u32_e32 v168, vcc, s14, v190
	v_cvt_pk_bf16_f32 v163, v166, v167
	v_cvt_pk_bf16_f32 v165, v170, v171
	v_cvt_pk_bf16_f32 v166, v172, v173
	v_cvt_pk_bf16_f32 v167, v174, v175
	v_addc_co_u32_e32 v169, vcc, 0, v191, vcc
	ds_write_b64 v193, v[160:161] offset:9216
	ds_write_b64 v193, v[162:163] offset:11520
	ds_write_b64 v193, v[164:165] offset:13824
	ds_write_b64 v194, v[166:167] offset:9216
	global_store_dwordx4 v[168:169], v[160:163], off
	global_store_dwordx4 v[168:169], v[164:167], off offset:16
	s_waitcnt lgkmcnt(0)
	s_barrier
	ds_read_b128 v[164:167], v195 offset:9216
	ds_read_b128 v[168:171], v195 offset:9280
	s_waitcnt vmcnt(56)
	v_lshlrev_b32_e32 v160, 16, v60
	v_and_b32_e32 v161, 0xffff0000, v60
	v_lshlrev_b32_e32 v162, 16, v61
	v_and_b32_e32 v163, 0xffff0000, v61
	ds_read_b128 v[172:175], v195 offset:11584
	ds_read_b128 v[198:201], v195 offset:13888
	s_waitcnt lgkmcnt(3)
	v_mfma_f32_16x16x32_bf16 v[160:163], v[48:51], v[164:167], v[160:163]
	v_lshlrev_b32_e32 v164, 16, v62
	v_and_b32_e32 v165, 0xffff0000, v62
	v_lshlrev_b32_e32 v166, 16, v63
	s_waitcnt lgkmcnt(2)
	v_mfma_f32_16x16x32_bf16 v[160:163], v[52:55], v[168:171], v[160:163]
	ds_read_b128 v[168:171], v195 offset:11520
	v_and_b32_e32 v167, 0xffff0000, v63
	ds_read_b128 v[202:205], v196 offset:9280
	s_cmpk_gt_u32 s34, 0x72
	s_waitcnt lgkmcnt(1)
	v_mfma_f32_16x16x32_bf16 v[164:167], v[48:51], v[168:171], v[164:167]
	v_lshlrev_b32_e32 v168, 16, v56
	v_and_b32_e32 v169, 0xffff0000, v56
	v_lshlrev_b32_e32 v170, 16, v57
	v_mfma_f32_16x16x32_bf16 v[164:167], v[52:55], v[172:175], v[164:167]
	ds_read_b128 v[172:175], v195 offset:13824
	v_and_b32_e32 v171, 0xffff0000, v57
	s_waitcnt lgkmcnt(0)
	s_nop 0
	v_mfma_f32_16x16x32_bf16 v[168:171], v[48:51], v[172:175], v[168:171]
	v_lshlrev_b32_e32 v172, 16, v58
	v_and_b32_e32 v173, 0xffff0000, v58
	v_lshlrev_b32_e32 v174, 16, v59
	v_mfma_f32_16x16x32_bf16 v[168:171], v[52:55], v[198:201], v[168:171]
	ds_read_b128 v[198:201], v196 offset:9216
	v_and_b32_e32 v175, 0xffff0000, v59
	s_waitcnt lgkmcnt(0)
	s_nop 0
	v_mfma_f32_16x16x32_bf16 v[172:175], v[48:51], v[198:201], v[172:175]
	v_mfma_f32_16x16x32_bf16 v[172:175], v[52:55], v[202:205], v[172:175]
	s_cbranch_scc1 .Lgs_916
	s_add_i32 s0, s4, 0xffffa000
	s_lshl_b64 s[8:9], s[0:1], 1
	v_lshl_add_u64 v[52:53], v[176:177], 0, s[8:9]
	v_lshl_add_u64 v[60:61], v[178:179], 0, s[8:9]
	global_load_dwordx4 v[48:51], v[52:53], off
	s_nop 0
	global_load_dwordx4 v[52:55], v[52:53], off offset:64
	s_nop 0
	global_load_dwordx4 v[56:59], v[60:61], off offset:16
	s_nop 0
	global_load_dwordx4 v[60:63], v[60:61], off
.Lgs_916:
	v_cvt_pk_bf16_f32 v160, v160, v161
	v_cvt_pk_bf16_f32 v161, v162, v163
	v_cvt_pk_bf16_f32 v162, v164, v165
	v_cvt_pk_bf16_f32 v164, v168, v169
	v_add_co_u32_e32 v168, vcc, s15, v190
	v_cvt_pk_bf16_f32 v163, v166, v167
	v_cvt_pk_bf16_f32 v165, v170, v171
	v_cvt_pk_bf16_f32 v166, v172, v173
	v_cvt_pk_bf16_f32 v167, v174, v175
	v_addc_co_u32_e32 v169, vcc, 0, v191, vcc
	ds_write_b64 v193, v[160:161]
	ds_write_b64 v193, v[162:163] offset:2304
	ds_write_b64 v193, v[164:165] offset:4608
	ds_write_b64 v194, v[166:167]
	global_store_dwordx4 v[168:169], v[160:163], off
	global_store_dwordx4 v[168:169], v[164:167], off offset:16
	s_waitcnt lgkmcnt(0)
	s_barrier
	ds_read_b128 v[164:167], v195
	ds_read_b128 v[168:171], v195 offset:64
	s_waitcnt vmcnt(56)
	v_lshlrev_b32_e32 v160, 16, v76
	v_and_b32_e32 v161, 0xffff0000, v76
	v_lshlrev_b32_e32 v162, 16, v77
	v_and_b32_e32 v163, 0xffff0000, v77
	ds_read_b128 v[172:175], v195 offset:2368
	ds_read_b128 v[198:201], v195 offset:4672
	s_waitcnt lgkmcnt(3)
	v_mfma_f32_16x16x32_bf16 v[160:163], v[64:67], v[164:167], v[160:163]
	v_lshlrev_b32_e32 v164, 16, v78
	v_and_b32_e32 v165, 0xffff0000, v78
	v_lshlrev_b32_e32 v166, 16, v79
	s_waitcnt lgkmcnt(2)
	v_mfma_f32_16x16x32_bf16 v[160:163], v[68:71], v[168:171], v[160:163]
	ds_read_b128 v[168:171], v195 offset:2304
	v_and_b32_e32 v167, 0xffff0000, v79
	ds_read_b128 v[202:205], v196 offset:64
	s_cmpk_gt_u32 s34, 0x71
	s_waitcnt lgkmcnt(1)
	v_mfma_f32_16x16x32_bf16 v[164:167], v[64:67], v[168:171], v[164:167]
	v_lshlrev_b32_e32 v168, 16, v72
	v_and_b32_e32 v169, 0xffff0000, v72
	v_lshlrev_b32_e32 v170, 16, v73
	v_mfma_f32_16x16x32_bf16 v[164:167], v[68:71], v[172:175], v[164:167]
	ds_read_b128 v[172:175], v195 offset:4608
	v_and_b32_e32 v171, 0xffff0000, v73
	s_waitcnt lgkmcnt(0)
	s_nop 0
	v_mfma_f32_16x16x32_bf16 v[168:171], v[64:67], v[172:175], v[168:171]
	v_lshlrev_b32_e32 v172, 16, v74
	v_and_b32_e32 v173, 0xffff0000, v74
	v_lshlrev_b32_e32 v174, 16, v75
	v_mfma_f32_16x16x32_bf16 v[168:171], v[68:71], v[198:201], v[168:171]
	ds_read_b128 v[198:201], v196
	v_and_b32_e32 v175, 0xffff0000, v75
	s_waitcnt lgkmcnt(0)
	s_nop 0
	v_mfma_f32_16x16x32_bf16 v[172:175], v[64:67], v[198:201], v[172:175]
	v_mfma_f32_16x16x32_bf16 v[172:175], v[68:71], v[202:205], v[172:175]
	s_cbranch_scc1 .Lgs_918
	s_add_i32 s0, s4, 0xffffb000
	s_lshl_b64 s[8:9], s[0:1], 1
	v_lshl_add_u64 v[68:69], v[176:177], 0, s[8:9]
	v_lshl_add_u64 v[76:77], v[178:179], 0, s[8:9]
	global_load_dwordx4 v[64:67], v[68:69], off
	s_nop 0
	global_load_dwordx4 v[68:71], v[68:69], off offset:64
	s_nop 0
	global_load_dwordx4 v[72:75], v[76:77], off offset:16
	s_nop 0
	global_load_dwordx4 v[76:79], v[76:77], off
.Lgs_918:
	v_cvt_pk_bf16_f32 v160, v160, v161
	v_cvt_pk_bf16_f32 v161, v162, v163
	v_cvt_pk_bf16_f32 v162, v164, v165
	v_cvt_pk_bf16_f32 v164, v168, v169
	v_add_co_u32_e32 v168, vcc, s16, v190
	v_cvt_pk_bf16_f32 v163, v166, v167
	v_cvt_pk_bf16_f32 v165, v170, v171
	v_cvt_pk_bf16_f32 v166, v172, v173
	v_cvt_pk_bf16_f32 v167, v174, v175
	v_addc_co_u32_e32 v169, vcc, 0, v191, vcc
	ds_write_b64 v193, v[160:161] offset:9216
	ds_write_b64 v193, v[162:163] offset:11520
	ds_write_b64 v193, v[164:165] offset:13824
	ds_write_b64 v194, v[166:167] offset:9216
	global_store_dwordx4 v[168:169], v[160:163], off
	global_store_dwordx4 v[168:169], v[164:167], off offset:16
	s_waitcnt lgkmcnt(0)
	s_barrier
	ds_read_b128 v[164:167], v195 offset:9216
	ds_read_b128 v[168:171], v195 offset:9280
	s_waitcnt vmcnt(56)
	v_lshlrev_b32_e32 v160, 16, v92
	v_and_b32_e32 v161, 0xffff0000, v92
	v_lshlrev_b32_e32 v162, 16, v93
	v_and_b32_e32 v163, 0xffff0000, v93
	ds_read_b128 v[172:175], v195 offset:11584
	ds_read_b128 v[198:201], v195 offset:13888
	s_waitcnt lgkmcnt(3)
	v_mfma_f32_16x16x32_bf16 v[160:163], v[80:83], v[164:167], v[160:163]
	v_lshlrev_b32_e32 v164, 16, v94
	v_and_b32_e32 v165, 0xffff0000, v94
	v_lshlrev_b32_e32 v166, 16, v95
	s_waitcnt lgkmcnt(2)
	v_mfma_f32_16x16x32_bf16 v[160:163], v[84:87], v[168:171], v[160:163]
	ds_read_b128 v[168:171], v195 offset:11520
	v_and_b32_e32 v167, 0xffff0000, v95
	ds_read_b128 v[202:205], v196 offset:9280
	s_cmpk_gt_u32 s34, 0x70
	s_waitcnt lgkmcnt(1)
	v_mfma_f32_16x16x32_bf16 v[164:167], v[80:83], v[168:171], v[164:167]
	v_lshlrev_b32_e32 v168, 16, v88
	v_and_b32_e32 v169, 0xffff0000, v88
	v_lshlrev_b32_e32 v170, 16, v89
	v_mfma_f32_16x16x32_bf16 v[164:167], v[84:87], v[172:175], v[164:167]
	ds_read_b128 v[172:175], v195 offset:13824
	v_and_b32_e32 v171, 0xffff0000, v89
	s_waitcnt lgkmcnt(0)
	s_nop 0
	v_mfma_f32_16x16x32_bf16 v[168:171], v[80:83], v[172:175], v[168:171]
	v_lshlrev_b32_e32 v172, 16, v90
	v_and_b32_e32 v173, 0xffff0000, v90
	v_lshlrev_b32_e32 v174, 16, v91
	v_mfma_f32_16x16x32_bf16 v[168:171], v[84:87], v[198:201], v[168:171]
	ds_read_b128 v[198:201], v196 offset:9216
	v_and_b32_e32 v175, 0xffff0000, v91
	s_waitcnt lgkmcnt(0)
	s_nop 0
	v_mfma_f32_16x16x32_bf16 v[172:175], v[80:83], v[198:201], v[172:175]
	v_mfma_f32_16x16x32_bf16 v[172:175], v[84:87], v[202:205], v[172:175]
	s_cbranch_scc1 .Lgs_920
	s_add_i32 s0, s4, 0xffffc000
	s_lshl_b64 s[8:9], s[0:1], 1
	v_lshl_add_u64 v[84:85], v[176:177], 0, s[8:9]
	v_lshl_add_u64 v[92:93], v[178:179], 0, s[8:9]
	global_load_dwordx4 v[80:83], v[84:85], off
	s_nop 0
	global_load_dwordx4 v[84:87], v[84:85], off offset:64
	s_nop 0
	global_load_dwordx4 v[88:91], v[92:93], off offset:16
	s_nop 0
	global_load_dwordx4 v[92:95], v[92:93], off
.Lgs_920:
	v_cvt_pk_bf16_f32 v160, v160, v161
	v_cvt_pk_bf16_f32 v161, v162, v163
	v_cvt_pk_bf16_f32 v162, v164, v165
	v_cvt_pk_bf16_f32 v164, v168, v169
	v_add_co_u32_e32 v168, vcc, s17, v190
	v_cvt_pk_bf16_f32 v163, v166, v167
	v_cvt_pk_bf16_f32 v165, v170, v171
	v_cvt_pk_bf16_f32 v166, v172, v173
	v_cvt_pk_bf16_f32 v167, v174, v175
	v_addc_co_u32_e32 v169, vcc, 0, v191, vcc
	ds_write_b64 v193, v[160:161]
	ds_write_b64 v193, v[162:163] offset:2304
	ds_write_b64 v193, v[164:165] offset:4608
	ds_write_b64 v194, v[166:167]
	global_store_dwordx4 v[168:169], v[160:163], off
	global_store_dwordx4 v[168:169], v[164:167], off offset:16
	s_waitcnt lgkmcnt(0)
	s_barrier
	ds_read_b128 v[164:167], v195
	ds_read_b128 v[168:171], v195 offset:64
	s_waitcnt vmcnt(56)
	v_lshlrev_b32_e32 v160, 16, v108
	v_and_b32_e32 v161, 0xffff0000, v108
	v_lshlrev_b32_e32 v162, 16, v109
	v_and_b32_e32 v163, 0xffff0000, v109
	ds_read_b128 v[172:175], v195 offset:2368
	ds_read_b128 v[198:201], v195 offset:4672
	s_waitcnt lgkmcnt(3)
	v_mfma_f32_16x16x32_bf16 v[160:163], v[96:99], v[164:167], v[160:163]
	v_lshlrev_b32_e32 v164, 16, v110
	v_and_b32_e32 v165, 0xffff0000, v110
	v_lshlrev_b32_e32 v166, 16, v111
	s_waitcnt lgkmcnt(2)
	v_mfma_f32_16x16x32_bf16 v[160:163], v[100:103], v[168:171], v[160:163]
	ds_read_b128 v[168:171], v195 offset:2304
	v_and_b32_e32 v167, 0xffff0000, v111
	ds_read_b128 v[202:205], v196 offset:64
	s_cmpk_gt_u32 s34, 0x6f
	s_waitcnt lgkmcnt(1)
	v_mfma_f32_16x16x32_bf16 v[164:167], v[96:99], v[168:171], v[164:167]
	v_lshlrev_b32_e32 v168, 16, v104
	v_and_b32_e32 v169, 0xffff0000, v104
	v_lshlrev_b32_e32 v170, 16, v105
	v_mfma_f32_16x16x32_bf16 v[164:167], v[100:103], v[172:175], v[164:167]
	ds_read_b128 v[172:175], v195 offset:4608
	v_and_b32_e32 v171, 0xffff0000, v105
	s_waitcnt lgkmcnt(0)
	s_nop 0
	v_mfma_f32_16x16x32_bf16 v[168:171], v[96:99], v[172:175], v[168:171]
	v_lshlrev_b32_e32 v172, 16, v106
	v_and_b32_e32 v173, 0xffff0000, v106
	v_lshlrev_b32_e32 v174, 16, v107
	v_mfma_f32_16x16x32_bf16 v[168:171], v[100:103], v[198:201], v[168:171]
	ds_read_b128 v[198:201], v196
	v_and_b32_e32 v175, 0xffff0000, v107
	s_waitcnt lgkmcnt(0)
	s_nop 0
	v_mfma_f32_16x16x32_bf16 v[172:175], v[96:99], v[198:201], v[172:175]
	v_mfma_f32_16x16x32_bf16 v[172:175], v[100:103], v[202:205], v[172:175]
	s_cbranch_scc1 .Lgs_922
	s_add_i32 s0, s4, 0xffffd000
	s_lshl_b64 s[8:9], s[0:1], 1
	v_lshl_add_u64 v[100:101], v[176:177], 0, s[8:9]
	v_lshl_add_u64 v[108:109], v[178:179], 0, s[8:9]
	global_load_dwordx4 v[96:99], v[100:101], off
	s_nop 0
	global_load_dwordx4 v[100:103], v[100:101], off offset:64
	s_nop 0
	global_load_dwordx4 v[104:107], v[108:109], off offset:16
	s_nop 0
	global_load_dwordx4 v[108:111], v[108:109], off
.Lgs_922:
	v_cvt_pk_bf16_f32 v160, v160, v161
	v_cvt_pk_bf16_f32 v161, v162, v163
	v_cvt_pk_bf16_f32 v162, v164, v165
	v_cvt_pk_bf16_f32 v164, v168, v169
	v_add_co_u32_e32 v168, vcc, s29, v190
	v_cvt_pk_bf16_f32 v163, v166, v167
	v_cvt_pk_bf16_f32 v165, v170, v171
	v_cvt_pk_bf16_f32 v166, v172, v173
	v_cvt_pk_bf16_f32 v167, v174, v175
	v_addc_co_u32_e32 v169, vcc, 0, v191, vcc
	ds_write_b64 v193, v[160:161] offset:9216
	ds_write_b64 v193, v[162:163] offset:11520
	ds_write_b64 v193, v[164:165] offset:13824
	ds_write_b64 v194, v[166:167] offset:9216
	global_store_dwordx4 v[168:169], v[160:163], off
	global_store_dwordx4 v[168:169], v[164:167], off offset:16
	s_waitcnt lgkmcnt(0)
	s_barrier
	ds_read_b128 v[164:167], v195 offset:9216
	ds_read_b128 v[168:171], v195 offset:9280
	s_waitcnt vmcnt(56)
	v_lshlrev_b32_e32 v160, 16, v124
	v_and_b32_e32 v161, 0xffff0000, v124
	v_lshlrev_b32_e32 v162, 16, v125
	v_and_b32_e32 v163, 0xffff0000, v125
	ds_read_b128 v[172:175], v195 offset:11584
	ds_read_b128 v[198:201], v195 offset:13888
	s_waitcnt lgkmcnt(3)
	v_mfma_f32_16x16x32_bf16 v[160:163], v[112:115], v[164:167], v[160:163]
	ds_read_b128 v[202:205], v196 offset:9280
	s_cmpk_gt_u32 s34, 0x6e
	s_waitcnt lgkmcnt(3)
	v_mfma_f32_16x16x32_bf16 v[164:167], v[116:119], v[168:171], v[160:163]
	ds_read_b128 v[168:171], v195 offset:11520
	s_nop 2
	v_lshlrev_b32_e32 v160, 16, v126
	v_and_b32_e32 v161, 0xffff0000, v126
	v_lshlrev_b32_e32 v162, 16, v127
	v_and_b32_e32 v163, 0xffff0000, v127
	s_waitcnt lgkmcnt(0)
	s_nop 0
	v_mfma_f32_16x16x32_bf16 v[160:163], v[112:115], v[168:171], v[160:163]
	v_mfma_f32_16x16x32_bf16 v[168:171], v[116:119], v[172:175], v[160:163]
	ds_read_b128 v[172:175], v195 offset:13824
	s_nop 5
	v_lshlrev_b32_e32 v160, 16, v120
	v_and_b32_e32 v161, 0xffff0000, v120
	v_lshlrev_b32_e32 v162, 16, v121
	v_and_b32_e32 v163, 0xffff0000, v121
	s_waitcnt lgkmcnt(0)
	s_nop 0
	v_mfma_f32_16x16x32_bf16 v[160:163], v[112:115], v[172:175], v[160:163]
	v_mfma_f32_16x16x32_bf16 v[172:175], v[116:119], v[198:201], v[160:163]
	ds_read_b128 v[198:201], v196 offset:9216
	s_nop 5
	v_lshlrev_b32_e32 v160, 16, v122
	v_and_b32_e32 v161, 0xffff0000, v122
	v_lshlrev_b32_e32 v162, 16, v123
	v_and_b32_e32 v163, 0xffff0000, v123
	s_waitcnt lgkmcnt(0)
	s_nop 0
	v_mfma_f32_16x16x32_bf16 v[160:163], v[112:115], v[198:201], v[160:163]
	v_mfma_f32_16x16x32_bf16 v[160:163], v[116:119], v[202:205], v[160:163]
	s_cbranch_scc1 .Lgs_924
	s_add_i32 s0, s4, 0xffffe000
	s_lshl_b64 s[8:9], s[0:1], 1
	v_lshl_add_u64 v[116:117], v[176:177], 0, s[8:9]
	v_lshl_add_u64 v[124:125], v[178:179], 0, s[8:9]
	global_load_dwordx4 v[112:115], v[116:117], off
	s_nop 0
	global_load_dwordx4 v[116:119], v[116:117], off offset:64
	s_nop 0
	global_load_dwordx4 v[120:123], v[124:125], off offset:16
	s_nop 0
	global_load_dwordx4 v[124:127], v[124:125], off
.Lgs_924:
	s_cmpk_gt_u32 s34, 0x77
	s_cselect_b64 s[8:9], -1, 0
	s_and_b64 vcc, exec, s[8:9]
	s_cbranch_vccnz .Lgs_927
	s_add_i32 s0, s10, s6
	s_add_i32 s0, s0, 0x10000
	v_cvt_pk_bf16_f32 v164, v164, v165
	v_cvt_pk_bf16_f32 v165, v166, v167
	v_cvt_pk_bf16_f32 v166, v168, v169
	v_cvt_pk_bf16_f32 v167, v170, v171
	v_cvt_pk_bf16_f32 v168, v172, v173
	v_cvt_pk_bf16_f32 v169, v174, v175
	v_cvt_pk_bf16_f32 v170, v160, v161
	v_cvt_pk_bf16_f32 v171, v162, v163
	v_lshl_add_u64 v[160:161], v[186:187], 0, s[0:1]
	ds_write_b64 v193, v[164:165]
	ds_write_b64 v193, v[166:167] offset:2304
	ds_write_b64 v193, v[168:169] offset:4608
	ds_write_b64 v194, v[170:171]
	global_store_dwordx4 v[160:161], v[164:167], off
	global_store_dwordx4 v[160:161], v[168:171], off offset:16
	s_waitcnt lgkmcnt(0)
	s_barrier
	ds_read_b128 v[164:167], v195
	ds_read_b128 v[168:171], v195 offset:64
	s_waitcnt vmcnt(56)
	v_lshlrev_b32_e32 v160, 16, v140
	v_and_b32_e32 v161, 0xffff0000, v140
	v_lshlrev_b32_e32 v162, 16, v141
	v_and_b32_e32 v163, 0xffff0000, v141
	ds_read_b128 v[172:175], v195 offset:2368
	ds_read_b128 v[198:201], v195 offset:4672
	s_waitcnt lgkmcnt(3)
	v_mfma_f32_16x16x32_bf16 v[160:163], v[128:131], v[164:167], v[160:163]
	s_cmpk_gt_u32 s34, 0x6d
	ds_read_b128 v[202:205], v196 offset:64
	s_waitcnt lgkmcnt(3)
	v_mfma_f32_16x16x32_bf16 v[164:167], v[132:135], v[168:171], v[160:163]
	ds_read_b128 v[168:171], v195 offset:2304
	s_nop 2
	v_lshlrev_b32_e32 v160, 16, v142
	v_and_b32_e32 v161, 0xffff0000, v142
	v_lshlrev_b32_e32 v162, 16, v143
	v_and_b32_e32 v163, 0xffff0000, v143
	s_waitcnt lgkmcnt(0)
	s_nop 0
	v_mfma_f32_16x16x32_bf16 v[160:163], v[128:131], v[168:171], v[160:163]
	v_mfma_f32_16x16x32_bf16 v[168:171], v[132:135], v[172:175], v[160:163]
	ds_read_b128 v[172:175], v195 offset:4608
	s_nop 5
	v_lshlrev_b32_e32 v160, 16, v136
	v_and_b32_e32 v161, 0xffff0000, v136
	v_lshlrev_b32_e32 v162, 16, v137
	v_and_b32_e32 v163, 0xffff0000, v137
	s_waitcnt lgkmcnt(0)
	s_nop 0
	v_mfma_f32_16x16x32_bf16 v[160:163], v[128:131], v[172:175], v[160:163]
	v_mfma_f32_16x16x32_bf16 v[172:175], v[132:135], v[198:201], v[160:163]
	ds_read_b128 v[198:201], v196
	s_nop 5
	v_lshlrev_b32_e32 v160, 16, v138
	v_and_b32_e32 v161, 0xffff0000, v138
	v_lshlrev_b32_e32 v162, 16, v139
	v_and_b32_e32 v163, 0xffff0000, v139
	s_waitcnt lgkmcnt(0)
	s_nop 0
	v_mfma_f32_16x16x32_bf16 v[160:163], v[128:131], v[198:201], v[160:163]
	v_mfma_f32_16x16x32_bf16 v[160:163], v[132:135], v[202:205], v[160:163]
	s_cbranch_scc1 .Lgs_927
	s_add_i32 s0, s4, 0xfffff000
	s_lshl_b64 s[24:25], s[0:1], 1
	v_lshl_add_u64 v[132:133], v[176:177], 0, s[24:25]
	v_lshl_add_u64 v[140:141], v[178:179], 0, s[24:25]
	global_load_dwordx4 v[128:131], v[132:133], off
	s_nop 0
	global_load_dwordx4 v[132:135], v[132:133], off offset:64
	s_nop 0
	global_load_dwordx4 v[136:139], v[140:141], off offset:16
	s_nop 0
	global_load_dwordx4 v[140:143], v[140:141], off
.Lgs_927:
	s_cmpk_gt_u32 s34, 0x76
	s_cbranch_scc1 .LBB0_907
	s_add_i32 s0, s10, s6
	s_add_i32 s0, s0, 0x12000
	v_cvt_pk_bf16_f32 v164, v164, v165
	v_cvt_pk_bf16_f32 v165, v166, v167
	v_cvt_pk_bf16_f32 v166, v168, v169
	v_cvt_pk_bf16_f32 v167, v170, v171
	v_cvt_pk_bf16_f32 v168, v172, v173
	v_cvt_pk_bf16_f32 v169, v174, v175
	v_cvt_pk_bf16_f32 v170, v160, v161
	v_cvt_pk_bf16_f32 v171, v162, v163
	v_lshl_add_u64 v[160:161], v[186:187], 0, s[0:1]
	ds_write_b64 v193, v[164:165] offset:9216
	ds_write_b64 v193, v[166:167] offset:11520
	ds_write_b64 v193, v[168:169] offset:13824
	ds_write_b64 v194, v[170:171] offset:9216
	global_store_dwordx4 v[160:161], v[164:167], off
	global_store_dwordx4 v[160:161], v[168:171], off offset:16
	s_waitcnt lgkmcnt(0)
	s_barrier
	ds_read_b128 v[164:167], v195 offset:9216
	ds_read_b128 v[168:171], v195 offset:9280
	s_waitcnt vmcnt(56)
	v_lshlrev_b32_e32 v160, 16, v156
	v_and_b32_e32 v161, 0xffff0000, v156
	v_lshlrev_b32_e32 v162, 16, v157
	v_and_b32_e32 v163, 0xffff0000, v157
	ds_read_b128 v[172:175], v195 offset:11584
	ds_read_b128 v[198:201], v195 offset:13888
	s_waitcnt lgkmcnt(3)
	v_mfma_f32_16x16x32_bf16 v[160:163], v[144:147], v[164:167], v[160:163]
	s_cmpk_gt_u32 s34, 0x6c
	ds_read_b128 v[202:205], v196 offset:9280
	s_waitcnt lgkmcnt(3)
	v_mfma_f32_16x16x32_bf16 v[164:167], v[148:151], v[168:171], v[160:163]
	ds_read_b128 v[168:171], v195 offset:11520
	s_nop 2
	v_lshlrev_b32_e32 v160, 16, v158
	v_and_b32_e32 v161, 0xffff0000, v158
	v_lshlrev_b32_e32 v162, 16, v159
	v_and_b32_e32 v163, 0xffff0000, v159
	s_waitcnt lgkmcnt(0)
	s_nop 0
	v_mfma_f32_16x16x32_bf16 v[160:163], v[144:147], v[168:171], v[160:163]
	v_mfma_f32_16x16x32_bf16 v[168:171], v[148:151], v[172:175], v[160:163]
	ds_read_b128 v[172:175], v195 offset:13824
	s_nop 5
	v_lshlrev_b32_e32 v160, 16, v152
	v_and_b32_e32 v161, 0xffff0000, v152
	v_lshlrev_b32_e32 v162, 16, v153
	v_and_b32_e32 v163, 0xffff0000, v153
	s_waitcnt lgkmcnt(0)
	s_nop 0
	v_mfma_f32_16x16x32_bf16 v[160:163], v[144:147], v[172:175], v[160:163]
	v_mfma_f32_16x16x32_bf16 v[172:175], v[148:151], v[198:201], v[160:163]
	ds_read_b128 v[198:201], v196 offset:9216
	s_nop 5
	v_lshlrev_b32_e32 v160, 16, v154
	v_and_b32_e32 v161, 0xffff0000, v154
	v_lshlrev_b32_e32 v162, 16, v155
	v_and_b32_e32 v163, 0xffff0000, v155
	s_waitcnt lgkmcnt(0)
	s_nop 0
	v_mfma_f32_16x16x32_bf16 v[160:163], v[144:147], v[198:201], v[160:163]
	v_mfma_f32_16x16x32_bf16 v[160:163], v[148:151], v[202:205], v[160:163]
	s_cbranch_scc1 .LBB0_907
	s_mov_b32 s5, s1
	s_lshl_b64 s[24:25], s[4:5], 1
	v_lshl_add_u64 v[148:149], v[176:177], 0, s[24:25]
	v_lshl_add_u64 v[156:157], v[178:179], 0, s[24:25]
	global_load_dwordx4 v[144:147], v[148:149], off
	s_nop 0
	global_load_dwordx4 v[148:151], v[148:149], off offset:64
	s_nop 0
	global_load_dwordx4 v[152:155], v[156:157], off offset:16
	s_nop 0
	global_load_dwordx4 v[156:159], v[156:157], off
	s_branch .LBB0_907
